# v7 + p2a/p2b grid barrier replaced by split-phase sync: WGs arrive after their FFT units (per-XCD count, last arriver writes back L2), wait+invalidate only before the YT transposes
# speedup vs baseline: 1.0118x; 1.0118x over previous
.Lfft_arrive:
	s_waitcnt vmcnt(0)
	s_barrier
	v_readlane_b32 s98, v255, 22
	v_readlane_b32 s99, v255, 23
	s_and_b64 s[98:99], exec, s[98:99]
	s_mov_b64 exec, s[98:99]
	s_cbranch_execz .Lfft_arr_done
	v_mov_b32_e32 v240, s70
	ds_read_b32 v241, v240
	v_readlane_b32 s98, v254, 54
	v_readlane_b32 s99, v254, 55
	v_mov_b32_e32 v242, 0x80
	s_nop 4
	global_atomic_add v243, v242, v236, s[98:99] sc0
	s_add_i32 s100, s4, 1
	s_waitcnt vmcnt(0) lgkmcnt(0)
	v_add_u32_e32 v243, 1, v243
	v_mul_lo_u32 v241, v241, s100
	v_cmp_eq_u32_e32 vcc, v243, v241
	s_and_b64 exec, exec, vcc
	s_cbranch_execz .Lfft_arr_done
	buffer_wbl2 sc1
	s_waitcnt vmcnt(0)
	v_mov_b32_e32 v242, 0x3480
	global_atomic_add v242, v236, s[76:77]
.Lfft_arr_done:
	s_mov_b64 exec, -1

.Lsw_p2a_done:
.LBB0_616:
	s_and_b64 s[0:1], s[66:67], s[14:15]
	s_and_b64 s[12:13], s[0:1], s[12:13]
	v_readlane_b32 s0, v255, 36
	s_add_i32 s0, s0, 4
	s_cmp_lt_i32 s0, s79
	s_cselect_b64 s[18:19], -1, 0
	s_and_b64 s[12:13], s[12:13], s[18:19]
	s_andn2_b64 vcc, exec, s[12:13]
	s_branch .LBB0_666
	s_waitcnt vmcnt(0)
	s_waitcnt vmcnt(0)
	s_barrier
	s_mov_b64 s[12:13], exec
	v_readlane_b32 s14, v255, 22
	v_readlane_b32 s15, v255, 23
	s_and_b64 s[14:15], s[12:13], s[14:15]
	s_mov_b64 exec, s[14:15]
	s_cbranch_execz .LBB0_665
	v_mov_b32_e32 v0, s70
	s_waitcnt vmcnt(0) expcnt(0) lgkmcnt(0)
	ds_read_b32 v3, v0
	ds_read_b32 v2, v0 offset:4
	s_waitcnt lgkmcnt(1)
	v_cmp_ne_u32_e32 vcc, 0, v3
	s_cbranch_vccnz .LBB0_633
	v_readlane_b32 s16, v254, 0
	v_readlane_b32 s17, v254, 1
	s_load_dwordx2 s[14:15], s[16:17], 0x4
	s_mov_b32 s5, 1
	s_waitcnt lgkmcnt(0)
	s_mul_i32 s1, s14, s3
	s_mul_i32 s1, s1, s15
	s_branch .LBB0_621

.LBB0_723:
	v_readlane_b32 s98, v255, 22
	v_readlane_b32 s99, v255, 23
	s_and_b64 s[98:99], exec, s[98:99]
	s_mov_b64 exec, s[98:99]
	s_cbranch_execz .Ltr_wait_done
	v_mov_b32_e32 v240, s70
	ds_read_b32 v241, v240 offset:4
	s_add_i32 s100, s4, 1
	v_mov_b32_e32 v242, 0x3480
	s_mov_b32 s101, 0
	s_waitcnt lgkmcnt(0)
	v_mul_lo_u32 v241, v241, s100
.Ltr_wait_spin:
	global_load_dword v243, v242, s[76:77] sc1
	s_waitcnt vmcnt(0)
	v_cmp_ge_u32_e32 vcc, v243, v241
	s_cbranch_vccnz .Ltr_wait_ok
	s_sleep 1
	s_add_u32 s101, s101, 1
	s_cmp_lt_u32 s101, 0x1000
	s_cbranch_scc1 .Ltr_wait_spin
.Ltr_wait_ok:
	buffer_inv sc1
	s_waitcnt vmcnt(0)
.Ltr_wait_done:
	s_mov_b64 exec, -1
	s_and_b64 vcc, exec, s[38:39]
	s_barrier
	s_cbranch_vccz .LBB0_725
	s_ashr_i32 s1, s24, 31
	s_lshr_b32 s1, s1, 29
	s_add_i32 s1, s24, s1
	s_ashr_i32 s10, s1, 3
	s_and_b32 s1, s1, -8
	s_ashr_i32 s0, s5, 3
	s_sub_i32 s1, s24, s1
	s_mul_i32 s0, s1, s0
	s_add_i32 s24, s0, s10
